# v32: v30 + MLA tile staging (5 LDS-DMAs) moved from the head of the tile step into the latency shadow of the first K-fragment reads (active waves)
# speedup vs baseline: 1.0035x; 1.0035x over previous
; #define LAS __attribute__((address_space(3)))
; #define SBAR() __builtin_amdgcn_sched_barrier(0)
; #define KRD2(f0, f1, ka_, m_) do { KRD(f0, kbo + ka_, (m_) * 128); KRD(f1, kbo + ka_, (m_) * 128 + 8192); } while (0)
; #define KMMA(f0, f1, q_) do { p0 = __builtin_amdgcn_mfma_f32_32x32x16_bf16(f0, q_, p0, 0, 0, 0); p1 = __builtin_amdgcn_mfma_f32_32x32x16_bf16(f1, q_, p1, 0, 0, 0); } while (0)
; #define KWAIT(n_) do { asm volatile("s_waitcnt lgkmcnt(" #n_ ")" ::: "memory"); SBAR(); } while (0)
; #define PRD3(f0, f1, qf, pa_, d_) do { KRD(f0, pbo + pa_, 0); KRD(f1, pbo + pa_, 4096); KRD(qf, qpo, (d_) * 1024); } while (0)
;     ...
;         if constexpr (ABL != 4) { if (j + 2 < NT) STAGE(j + 2, bn2); }
;         if (active && j < wnt) {
;             const LAS unsigned char* Ks = lds + buf * BUF; const LAS unsigned char* Ps = Ks + SHM_K + SHM_V;
;             f32x16 p0, p1;
; #pragma unroll
;             for (int r = 0; r < 16; ++r) { p0[r] = 0.f; p1[r] = 0.f; }
;             if constexpr (ABL != 3) {
;             const int kbo = (int)(uintptr_t)Ks;
;             bf16x8 fa0, fa1, fb0, fb1;
;     ...
;             KRD2(fa0, fa1, ka0, 0); KRD2(fb0, fb1, ka1, 0);
;             KWAIT(2); KMMA(fa0, fa1, qr[0]); SBAR(); KRD2(fa0, fa1, ka2, 0);
;             KWAIT(2); KMMA(fb0, fb1, qr[1]); SBAR(); KRD2(fb0, fb1, ka3, 0);
;             KWAIT(2); KMMA(fa0, fa1, qr[2]); SBAR(); KRD2(fa0, fa1, ka0, 1);
;             KWAIT(2); KMMA(fb0, fb1, qr[3]); SBAR(); KRD2(fb0, fb1, ka1, 1);
;             KWAIT(2); KMMA(fa0, fa1, qr[4]); SBAR(); KRD2(fa0, fa1, ka2, 1);
;             KWAIT(2); KMMA(fb0, fb1, qr[5]); SBAR(); KRD2(fb0, fb1, ka3, 1);
;             if constexpr (DPE == 64) {
;                 const int pbo = (int)(uintptr_t)Ps; const int qpo = (int)(uintptr_t)qpl; bf16x8 qfa, qfb;
;     ...
;                 KWAIT(2); KMMA(fa0, fa1, qr[6]); SBAR(); PRD3(fa0, fa1, qfa, pa_0, 0);
;                 KWAIT(3); KMMA(fb0, fb1, qr[7]); SBAR(); PRD3(fb0, fb1, qfb, pa_1, 1);
;                 KWAIT(3); KMMA(fa0, fa1, qfa); SBAR(); PRD3(fa0, fa1, qfa, pa_2, 2);
;                 KWAIT(3); KMMA(fb0, fb1, qfb); SBAR(); PRD3(fb0, fb1, qfb, pa_3, 3);
;                 KWAIT(3); KMMA(fa0, fa1, qfa); SBAR();
.LBB0_1185:
	s_add_i32 s0, s26, 2
	s_cmp_ge_u32 s0, s56
	s_cselect_b64 s[48:49], -1, 0
	s_mul_i32 s27, s25, 0xa000
	s_cmp_ge_i32 s26, s57
	s_cselect_b64 s[0:1], -1, 0
	s_xor_b64 s[50:51], s[46:47], -1
	s_or_b64 s[0:1], s[50:51], s[0:1]
	s_and_b64 vcc, exec, s[0:1]
	s_cbranch_vccz .Latt_qk
	s_and_b64 vcc, exec, s[48:49]
	s_cbranch_vccnz .LBB0_1193
	s_add_i32 s0, s27, 0xffff6000
	s_cmp_lg_u32 s25, 0
	s_cselect_b32 s0, s0, 0x14000
	s_add_i32 s0, s58, s0
	v_lshl_add_u64 v[4:5], s[34:35], 0, v[158:159]
	s_mov_b32 m0, s0
	s_nop 0
	global_load_lds_dwordx4 v[4:5], off
	v_lshl_add_u64 v[4:5], s[34:35], 0, v[160:161]
	s_add_i32 m0, s0, 0x2000
	s_nop 0
	global_load_lds_dwordx4 v[4:5], off
	v_lshl_add_u64 v[4:5], s[34:35], 0, v[156:157]
	s_add_i32 m0, s0, 0x4000
	s_nop 0
	global_load_lds_dwordx4 v[4:5], off
	v_lshl_add_u64 v[4:5], s[34:35], 0, v[154:155]
	s_add_i32 m0, s0, 0x6000
	s_nop 0
	global_load_lds_dwordx4 v[4:5], off
	v_lshl_add_u64 v[4:5], s[34:35], 0, v[152:153]
	s_add_i32 m0, s0, 0x8000
	s_nop 0
	global_load_lds_dwordx4 v[4:5], off
	s_branch .LBB0_1193
.Latt_qk:
	s_add_i32 s0, s27, 0
	s_add_i32 s1, s0, 0x8000
	v_add_u32_e32 v196, s0, v174
	v_add_u32_e32 v197, s0, v175
	v_add_u32_e32 v198, s0, v176
	v_add_u32_e32 v199, s0, v177
	v_add_u32_e32 v162, s1, v172
	v_add_u32_e32 v163, s1, v178
	v_add_u32_e32 v164, s1, v173
	v_add_u32_e32 v165, s1, v179
	ds_read_b128 v[4:7], v196 offset:0
	ds_read_b128 v[8:11], v196 offset:8192
	ds_read_b128 v[12:15], v197 offset:0
	ds_read_b128 v[188:191], v197 offset:8192
	ds_read_b128 v[192:195], v198 offset:0
	ds_read_b128 v[214:217], v198 offset:8192
	ds_read_b128 v[218:221], v199 offset:0
	ds_read_b128 v[234:237], v199 offset:8192
	s_and_b64 vcc, exec, s[48:49]
	s_cbranch_vccnz .Latt_nostage
	s_add_i32 s0, s27, 0xffff6000
	s_cmp_lg_u32 s25, 0
	s_cselect_b32 s0, s0, 0x14000
	s_add_i32 s0, s58, s0
	v_lshl_add_u64 v[16:17], s[34:35], 0, v[158:159]
	s_mov_b32 m0, s0
	s_nop 0
	global_load_lds_dwordx4 v[16:17], off
	v_lshl_add_u64 v[16:17], s[34:35], 0, v[160:161]
	s_add_i32 m0, s0, 0x2000
	s_nop 0
	global_load_lds_dwordx4 v[16:17], off
	v_lshl_add_u64 v[16:17], s[34:35], 0, v[156:157]
	s_add_i32 m0, s0, 0x4000
	s_nop 0
	global_load_lds_dwordx4 v[16:17], off
	v_lshl_add_u64 v[16:17], s[34:35], 0, v[154:155]
	s_add_i32 m0, s0, 0x6000
	s_nop 0
	global_load_lds_dwordx4 v[16:17], off
	v_lshl_add_u64 v[16:17], s[34:35], 0, v[152:153]
	s_add_i32 m0, s0, 0x8000
	s_nop 0
	global_load_lds_dwordx4 v[16:17], off
.Latt_nostage:
	s_waitcnt lgkmcnt(6)
	v_mfma_f32_32x32x16_bf16 v[82:97], v[4:7], v[114:117], 0
	v_mfma_f32_32x32x16_bf16 v[98:113], v[8:11], v[114:117], 0
	ds_read_b128 v[238:241], v196 offset:128
	ds_read_b128 v[242:245], v196 offset:8320
	s_waitcnt lgkmcnt(6)
	v_mfma_f32_32x32x16_bf16 v[82:97], v[12:15], v[118:121], v[82:97]
	v_mfma_f32_32x32x16_bf16 v[98:113], v[188:191], v[118:121], v[98:113]
	ds_read_b128 v[246:249], v197 offset:128
	ds_read_b128 v[222:225], v197 offset:8320
	s_waitcnt lgkmcnt(6)
	v_mfma_f32_32x32x16_bf16 v[82:97], v[192:195], v[122:125], v[82:97]
	v_mfma_f32_32x32x16_bf16 v[98:113], v[214:217], v[122:125], v[98:113]
	ds_read_b128 v[4:7], v198 offset:128
	ds_read_b128 v[8:11], v198 offset:8320
	s_waitcnt lgkmcnt(6)
	v_mfma_f32_32x32x16_bf16 v[82:97], v[218:221], v[126:129], v[82:97]
	v_mfma_f32_32x32x16_bf16 v[98:113], v[234:237], v[126:129], v[98:113]
	ds_read_b128 v[12:15], v199 offset:128
	ds_read_b128 v[188:191], v199 offset:8320
	s_waitcnt lgkmcnt(6)
	v_mfma_f32_32x32x16_bf16 v[82:97], v[238:241], v[130:133], v[82:97]
	v_mfma_f32_32x32x16_bf16 v[98:113], v[242:245], v[130:133], v[98:113]
	ds_read_b128 v[192:195], v162
	ds_read_b128 v[214:217], v162 offset:4096
	ds_read_b128 v[210:213], v183 offset:0
	s_waitcnt lgkmcnt(7)
	v_mfma_f32_32x32x16_bf16 v[82:97], v[246:249], v[134:137], v[82:97]
	v_mfma_f32_32x32x16_bf16 v[98:113], v[222:225], v[134:137], v[98:113]
	ds_read_b128 v[218:221], v163
	ds_read_b128 v[234:237], v163 offset:4096
	ds_read_b128 v[202:205], v183 offset:1024
	s_waitcnt lgkmcnt(8)
	v_mfma_f32_32x32x16_bf16 v[82:97], v[4:7], v[138:141], v[82:97]
	v_mfma_f32_32x32x16_bf16 v[98:113], v[8:11], v[138:141], v[98:113]
	ds_read_b128 v[238:241], v164
	ds_read_b128 v[242:245], v164 offset:4096
	ds_read_b128 v[230:233], v183 offset:2048
	s_waitcnt lgkmcnt(9)
	v_mfma_f32_32x32x16_bf16 v[82:97], v[12:15], v[142:145], v[82:97]
	v_mfma_f32_32x32x16_bf16 v[98:113], v[188:191], v[142:145], v[98:113]
	ds_read_b128 v[246:249], v165
	ds_read_b128 v[222:225], v165 offset:4096
	ds_read_b128 v[206:209], v183 offset:3072
	s_waitcnt lgkmcnt(9)
	v_mfma_f32_32x32x16_bf16 v[82:97], v[192:195], v[210:213], v[82:97]
	v_mfma_f32_32x32x16_bf16 v[98:113], v[214:217], v[210:213], v[98:113]
	s_waitcnt lgkmcnt(6)
	v_mfma_f32_32x32x16_bf16 v[82:97], v[218:221], v[202:205], v[82:97]
	v_mfma_f32_32x32x16_bf16 v[98:113], v[234:237], v[202:205], v[98:113]
	s_waitcnt lgkmcnt(3)
	v_mfma_f32_32x32x16_bf16 v[82:97], v[238:241], v[230:233], v[82:97]
	v_mfma_f32_32x32x16_bf16 v[98:113], v[242:245], v[230:233], v[98:113]
	s_waitcnt lgkmcnt(0)
; #define SBAR() __builtin_amdgcn_sched_barrier(0)
; DI int crow(int r, int hi) { return (r & 3) + 8 * (r >> 2) + 4 * hi; }
; #define KMMA(f0, f1, q_) do { p0 = __builtin_amdgcn_mfma_f32_32x32x16_bf16(f0, q_, p0, 0, 0, 0); p1 = __builtin_amdgcn_mfma_f32_32x32x16_bf16(f1, q_, p1, 0, 0, 0); } while (0)
; #define KWAIT(n_) do { asm volatile("s_waitcnt lgkmcnt(" #n_ ")" ::: "memory"); SBAR(); } while (0)
;     ...
;                 KWAIT(3); KMMA(fa0, fa1, qfa); SBAR();
;                 KWAIT(0); KMMA(fb0, fb1, qfb);
;     ...
;             } else {
;                 KWAIT(2); KMMA(fa0, fa1, qr[6]); SBAR();
;                 KWAIT(0); KMMA(fb0, fb1, qr[7]);
;             }
;     ...
;             } else { asm volatile("" : "+v"(p0), "+v"(p1)); }
;             float alpha = 1.f;
;             if constexpr (ABL != 1) {
;             float pmax = p0[0];
; #pragma unroll
;             for (int r = 1; r < 16; ++r) pmax = fmaxf(pmax, p0[r]);
; #pragma unroll
;             for (int r = 0; r < 16; ++r) pmax = fmaxf(pmax, p1[r]);
;             { auto rr = __builtin_amdgcn_permlane32_swap(__float_as_uint(pmax), __float_as_uint(pmax), false, false); pmax = fmaxf(__uint_as_float(rr[0]), __uint_as_float(rr[1])); }
;             float mn;
;             if (__all(pmax - m_reg <= thr_raw)) { mn = m_reg; alpha = 1.f; }
;             else { mn = fmaxf(m_reg, pmax); alpha = __builtin_amdgcn_exp2f((m_reg - mn) * C); m_reg = mn; }
;             const float mnC = -mn * C;
; #pragma unroll
;             for (int r = 0; r < 16; ++r) { p0[r] = __builtin_amdgcn_exp2f(fmaf(p0[r], C, mnC)); p1[r] = __builtin_amdgcn_exp2f(fmaf(p1[r], C, mnC)); }
;             float ps = 0.f;
; #pragma unroll
;             for (int r = 0; r < 16; ++r) ps += p0[r] + p1[r];
;             { auto rr = __builtin_amdgcn_permlane32_swap(__float_as_uint(ps), __float_as_uint(ps), false, false); ps = __uint_as_float(rr[0]) + __uint_as_float(rr[1]); }
;             l_reg = l_reg * alpha + ps;
;             }
;             bf16x8 pa0, pa1, pa2, pa3;
;     ...
;             PK4(p0, 0, pa0); PK4(p0, 8, pa1); PK4(p1, 0, pa2); PK4(p1, 8, pa3);
;     ...
;             if (__any(alpha < 1.f)) { if (hi == 0) al_l[r32] = alpha; asm volatile("s_waitcnt lgkmcnt(0)" ::: "memory");
; #pragma unroll
;                 for (int r = 0; r < 16; ++r) { const float a = al_l[crow(r, hi)];
; #pragma unroll
;                     for (int d = 0; d < 4; ++d) o[d][r] *= a; } }
	v_mfma_f32_32x32x16_bf16 v[82:97], v[246:249], v[206:209], v[82:97]
	v_mfma_f32_32x32x16_bf16 v[98:113], v[222:225], v[206:209], v[98:113]
	s_mov_b32 s0, 0x42ddb3d8
	s_nop 10
	v_max_f32_e32 v2, v83, v83
	v_max_f32_e32 v4, v82, v82
	v_max_f32_e32 v2, v4, v2
	v_max3_f32 v2, v2, v84, v85
	v_max3_f32 v2, v2, v86, v87
	v_max3_f32 v2, v2, v88, v89
	v_max3_f32 v2, v2, v90, v91
	v_max3_f32 v2, v2, v92, v93
	v_max3_f32 v2, v2, v94, v95
	v_max3_f32 v2, v2, v96, v97
	v_max_f32_e32 v4, v185, v185
	v_max3_f32 v2, v2, v98, v99
	v_max3_f32 v2, v2, v100, v101
	v_max3_f32 v2, v2, v102, v103
	v_max3_f32 v2, v2, v104, v105
	v_max3_f32 v2, v2, v106, v107
	v_max3_f32 v2, v2, v108, v109
	v_max3_f32 v2, v2, v110, v111
	v_max3_f32 v2, v2, v112, v113
	v_mov_b32_e32 v5, v2
	s_nop 1
	v_permlane32_swap_b32_e32 v2, v5
	v_max_f32_e32 v5, v5, v5
	v_max_f32_e32 v2, v2, v2
	v_max_f32_e32 v2, v2, v5
	v_sub_f32_e32 v5, v2, v185
	v_cmp_ge_f32_e32 vcc, s0, v5
	s_cmp_eq_u64 vcc, exec
	v_max_f32_e32 v2, v4, v2
	s_cselect_b64 vcc, -1, 0
	v_sub_f32_e32 v4, v185, v2
	v_cndmask_b32_e32 v185, v2, v185, vcc
	v_mul_f32_e32 v2, 0xbdd53b94, v185
	v_fmamk_f32 v5, v82, 0x3dd53b94, v2
	v_fmamk_f32 v6, v98, 0x3dd53b94, v2
	v_fmamk_f32 v7, v83, 0x3dd53b94, v2
	v_fmamk_f32 v8, v99, 0x3dd53b94, v2
	v_fmamk_f32 v10, v100, 0x3dd53b94, v2
	v_exp_f32_e32 v5, v5
	v_exp_f32_e32 v100, v6
	v_fmamk_f32 v9, v84, 0x3dd53b94, v2
	v_fmamk_f32 v12, v101, 0x3dd53b94, v2
	v_exp_f32_e32 v6, v7
	v_exp_f32_e32 v101, v8
	v_fmamk_f32 v11, v85, 0x3dd53b94, v2
	v_fmamk_f32 v14, v102, 0x3dd53b94, v2
	v_exp_f32_e32 v7, v9
	v_exp_f32_e32 v102, v10
	v_fmamk_f32 v13, v86, 0x3dd53b94, v2
	v_fmamk_f32 v15, v87, 0x3dd53b94, v2
	v_fmamk_f32 v16, v103, 0x3dd53b94, v2
	v_fmamk_f32 v17, v88, 0x3dd53b94, v2
	v_fmamk_f32 v82, v104, 0x3dd53b94, v2
	v_fmamk_f32 v83, v89, 0x3dd53b94, v2
	v_fmamk_f32 v84, v105, 0x3dd53b94, v2
	v_fmamk_f32 v85, v90, 0x3dd53b94, v2
	v_fmamk_f32 v86, v106, 0x3dd53b94, v2
	v_fmamk_f32 v87, v91, 0x3dd53b94, v2
	v_fmamk_f32 v88, v107, 0x3dd53b94, v2
	v_fmamk_f32 v89, v92, 0x3dd53b94, v2
	v_fmamk_f32 v90, v108, 0x3dd53b94, v2
	v_fmamk_f32 v91, v93, 0x3dd53b94, v2
	v_fmamk_f32 v92, v109, 0x3dd53b94, v2
	v_fmamk_f32 v93, v94, 0x3dd53b94, v2
	v_fmamk_f32 v94, v110, 0x3dd53b94, v2
	v_fmamk_f32 v95, v95, 0x3dd53b94, v2
	v_fmamk_f32 v98, v111, 0x3dd53b94, v2
	v_fmamk_f32 v96, v96, 0x3dd53b94, v2
	v_fmamk_f32 v99, v112, 0x3dd53b94, v2
	v_fmamk_f32 v97, v97, 0x3dd53b94, v2
	v_fmac_f32_e32 v2, 0x3dd53b94, v113
	v_exp_f32_e32 v8, v11
	v_exp_f32_e32 v103, v12
	v_exp_f32_e32 v9, v13
	v_exp_f32_e32 v14, v14
	v_exp_f32_e32 v12, v83
	v_exp_f32_e32 v83, v84
	v_exp_f32_e32 v84, v86
	v_exp_f32_e32 v86, v88
	v_exp_f32_e32 v88, v90
	v_exp_f32_e32 v90, v92
	v_exp_f32_e32 v92, v94
	v_exp_f32_e32 v94, v98
	v_exp_f32_e32 v98, v2
	v_add_f32_e32 v2, v5, v100
	v_exp_f32_e32 v10, v15
	v_exp_f32_e32 v15, v16
	v_add_f32_e32 v16, v6, v101
	v_add_f32_e32 v2, 0, v2
	v_exp_f32_e32 v11, v17
	v_exp_f32_e32 v82, v82
	v_add_f32_e32 v17, v7, v102
	v_add_f32_e32 v2, v16, v2
	v_exp_f32_e32 v13, v85
	v_exp_f32_e32 v85, v87
	v_exp_f32_e32 v87, v89
	v_exp_f32_e32 v89, v91
	v_exp_f32_e32 v91, v93
	v_exp_f32_e32 v93, v95
	v_exp_f32_e32 v95, v96
	v_exp_f32_e32 v96, v99
	v_add_f32_e32 v99, v8, v103
	v_add_f32_e32 v2, v17, v2
	v_add_f32_e32 v104, v9, v14
	v_add_f32_e32 v2, v99, v2
	v_add_f32_e32 v105, v10, v15
	v_add_f32_e32 v2, v104, v2
	v_add_f32_e32 v106, v11, v82
	v_add_f32_e32 v2, v105, v2
	v_add_f32_e32 v2, v106, v2
	v_add_f32_e32 v16, v12, v83
	v_add_f32_e32 v2, v16, v2
	v_add_f32_e32 v16, v13, v84
	v_add_f32_e32 v2, v16, v2
	v_add_f32_e32 v16, v85, v86
	v_add_f32_e32 v2, v16, v2
	v_add_f32_e32 v16, v87, v88
	v_exp_f32_e32 v97, v97
	v_add_f32_e32 v2, v16, v2
	v_add_f32_e32 v16, v89, v90
	v_mul_f32_e32 v4, 0x3dd53b94, v4
	v_add_f32_e32 v2, v16, v2
	v_add_f32_e32 v16, v91, v92
	v_exp_f32_e32 v4, v4
	v_add_f32_e32 v2, v16, v2
	v_add_f32_e32 v16, v93, v94
	v_add_f32_e32 v2, v16, v2
	v_add_f32_e32 v16, v95, v96
	v_add_f32_e32 v2, v16, v2
	v_add_f32_e32 v16, v97, v98
	v_add_f32_e32 v16, v16, v2
	v_cndmask_b32_e64 v2, v4, 1.0, vcc
	v_mov_b32_e32 v17, v16
	v_cvt_pk_bf16_f32 v4, v5, v6
	v_cvt_pk_bf16_f32 v5, v7, v8
	v_cvt_pk_bf16_f32 v6, v9, v10
	v_cvt_pk_bf16_f32 v7, v11, v12
	v_cvt_pk_bf16_f32 v8, v13, v85
	v_cvt_pk_bf16_f32 v9, v87, v89
	v_cvt_pk_bf16_f32 v10, v91, v93
	v_cvt_pk_bf16_f32 v11, v95, v97
	v_cvt_pk_bf16_f32 v12, v100, v101
	v_cvt_pk_bf16_f32 v13, v102, v103
	v_cvt_pk_bf16_f32 v14, v14, v15
	v_cvt_pk_bf16_f32 v15, v82, v83
	v_cvt_pk_bf16_f32 v82, v84, v86
	v_cvt_pk_bf16_f32 v83, v88, v90
	v_cvt_pk_bf16_f32 v84, v92, v94
	v_cvt_pk_bf16_f32 v85, v96, v98
	v_permlane32_swap_b32_e32 v16, v17
	v_permlane32_swap_b32_e32 v4, v6
	v_permlane32_swap_b32_e32 v5, v7
	v_permlane32_swap_b32_e32 v8, v10
	v_permlane32_swap_b32_e32 v9, v11
	v_permlane32_swap_b32_e32 v12, v14
	v_permlane32_swap_b32_e32 v13, v15
	v_permlane32_swap_b32_e32 v82, v84
	v_permlane32_swap_b32_e32 v83, v85
	v_cmp_gt_f32_e32 vcc, 1.0, v2
	s_cbranch_vccz .LBB0_1192
	s_and_saveexec_b64 s[0:1], s[38:39]
	ds_write_b32 v184, v2 offset:128
	s_or_b64 exec, exec, s[0:1]
	s_waitcnt lgkmcnt(0)
	v_add_u32_e32 v98, s55, v171
	ds_read_b128 v[86:89], v98 offset:224
	ds_read_b128 v[90:93], v98 offset:192
	ds_read_b128 v[94:97], v98 offset:160
	ds_read_b128 v[98:101], v98 offset:128
	s_waitcnt lgkmcnt(0)
	v_pk_mul_f32 v[78:79], v[78:79], v[86:87]
	v_pk_mul_f32 v[74:75], v[74:75], v[90:91]
	v_pk_mul_f32 v[70:71], v[70:71], v[94:95]
	v_pk_mul_f32 v[80:81], v[80:81], v[88:89]
	v_pk_mul_f32 v[76:77], v[76:77], v[92:93]
	v_pk_mul_f32 v[72:73], v[72:73], v[96:97]
	v_pk_mul_f32 v[68:69], v[68:69], v[100:101]
	v_pk_mul_f32 v[66:67], v[66:67], v[98:99]
	v_pk_mul_f32 v[62:63], v[62:63], v[86:87]
	v_pk_mul_f32 v[58:59], v[58:59], v[90:91]
	v_pk_mul_f32 v[54:55], v[54:55], v[94:95]
	v_pk_mul_f32 v[64:65], v[64:65], v[88:89]
	v_pk_mul_f32 v[60:61], v[60:61], v[92:93]
	v_pk_mul_f32 v[56:57], v[56:57], v[96:97]
	v_pk_mul_f32 v[52:53], v[52:53], v[100:101]
	v_pk_mul_f32 v[50:51], v[50:51], v[98:99]
	v_pk_mul_f32 v[46:47], v[46:47], v[86:87]
	v_pk_mul_f32 v[42:43], v[42:43], v[90:91]
	v_pk_mul_f32 v[38:39], v[38:39], v[94:95]
	v_pk_mul_f32 v[48:49], v[48:49], v[88:89]
	v_pk_mul_f32 v[44:45], v[44:45], v[92:93]
	v_pk_mul_f32 v[40:41], v[40:41], v[96:97]
	v_pk_mul_f32 v[36:37], v[36:37], v[100:101]
	v_pk_mul_f32 v[34:35], v[34:35], v[98:99]
	v_pk_mul_f32 v[30:31], v[30:31], v[86:87]
	v_pk_mul_f32 v[26:27], v[26:27], v[90:91]
	v_pk_mul_f32 v[22:23], v[22:23], v[94:95]
	v_pk_mul_f32 v[32:33], v[32:33], v[88:89]
	v_pk_mul_f32 v[28:29], v[28:29], v[92:93]
	v_pk_mul_f32 v[24:25], v[24:25], v[96:97]
	v_pk_mul_f32 v[20:21], v[20:21], v[100:101]
	v_pk_mul_f32 v[18:19], v[18:19], v[98:99]

; #define PG8_STAGE(bufoff, gbase, voff) do { _Pragma("unroll") for (int _i = 0; _i < 2; ++_i) \
;         __builtin_amdgcn_global_load_lds((const unsigned*)((const char*)(gbase) + (voff)[_i]), (PG8_LAS unsigned*)(lds + (bufoff) + ldsw + _i * 8192), 16, 0, 0); } while (0)
; #define PG8_LDA(dst, b, h) do { _Pragma("unroll") for (int m = 0; m < 4; ++m) _Pragma("unroll") for (int k = 0; k < 2; ++k) dst[m][k] = *(const PG8_LAS bf16x8*)(lds + PG8_SA(b, h) + aoff + m * 2048 + k * 1024); } while (0)
; #define PG8_LDB(dst, b, h) do { _Pragma("unroll") for (int n = 0; n < 2; ++n) _Pragma("unroll") for (int k = 0; k < 2; ++k) dst[n][k] = *(const PG8_LAS bf16x8*)(lds + PG8_SB(b, h) + boff + n * 2048 + k * 1024); } while (0)
; #define PG8_MMA(ai, bj, At, Bt) do { __builtin_amdgcn_s_setprio(1); _Pragma("unroll") for (int m = 0; m < 4; ++m) _Pragma("unroll") for (int n = 0; n < 2; ++n) _Pragma("unroll") for (int k = 0; k < 2; ++k) \
;         acc[ai][bj][m][n] = __builtin_amdgcn_mfma_f32_16x16x32_bf16(Bt[n][k], At[m][k], acc[ai][bj][m][n], 0, 0, 0); __builtin_amdgcn_s_setprio(0); } while (0)
; #define PG8_WAIT_V(n) asm volatile("s_waitcnt vmcnt(" #n ")" ::: "memory")
; #define PG8_WAIT_L(n) asm volatile("s_waitcnt lgkmcnt(" #n ")" ::: "memory")
; #define PG8_BAR __builtin_amdgcn_s_barrier()
; #define PG8_SCHED __builtin_amdgcn_sched_barrier(0)
; template <class Epi, class Sched, bool ALIGN_EPI = false, bool SP2 = false>
; __device__ __forceinline__ void gemm_phase(PG8_LAS unsigned char* lds, const Gemm g, const Sched& S, const Epi& E) {
;     ...
;             PG8_LDB(B0, 0, 0); PG8_LDB(B1, 0, 1); PG8_SCHED; PG8_LDA(At, 0, 0); PG8_STAGE(PG8_SA(1, 1), a1 + hstep, voffA);
;             PG8_WAIT_V(8); PG8_WAIT_L(0); PG8_BAR; PG8_MMA(0, 0, At, B0); PG8_MMA(0, 1, At, B1); PG8_BAR; PG8_SCHED;
;             PG8_LDA(At, 0, 1); PG8_STAGE(PG8_SB(0, 0), b2, voffB); PG8_STAGE(PG8_SB(0, 1), b2 + hstep, voffB); PG8_STAGE(PG8_SA(0, 0), a2, voffA);
;             PG8_WAIT_V(8); PG8_WAIT_L(0); PG8_BAR; PG8_MMA(1, 0, At, B0); PG8_MMA(1, 1, At, B1); PG8_BAR; PG8_SCHED;
.LBB0_1624:
	s_setprio 0
	ds_read_b128 v[142:145], v210
	ds_read_b128 v[150:153], v210 offset:1024
	ds_read_b128 v[154:157], v210 offset:2048
	ds_read_b128 v[158:161], v210 offset:3072
	ds_read_b128 v[162:165], v210 offset:16384
	ds_read_b128 v[166:169], v210 offset:17408
	ds_read_b128 v[170:173], v210 offset:18432
	ds_read_b128 v[174:177], v210 offset:19456
	ds_read_b128 v[178:181], v149
	ds_read_b128 v[182:185], v149 offset:1024
	ds_read_b128 v[186:189], v149 offset:2048
	ds_read_b128 v[190:193], v149 offset:3072
	ds_read_b128 v[194:197], v149 offset:4096
	ds_read_b128 v[198:201], v149 offset:5120
	ds_read_b128 v[202:205], v149 offset:6144
	ds_read_b128 v[206:209], v149 offset:7168
	s_add_u32 s0, s56, 0xfff00080
	s_addc_u32 s1, s57, -1
	s_add_i32 s63, 0, 0x10000
	s_cmp_eq_u32 s62, 60
	s_cselect_b32 s27, s51, s1
	s_cselect_b32 s26, s50, s0
	s_cselect_b32 s1, s53, s49
	s_cselect_b32 s0, s52, s47
	s_add_i32 s66, 0, 0x14000
	s_add_u32 s100, s56, 0xfff00000
	s_addc_u32 s101, s57, -1
	s_mov_b32 m0, s58
	s_nop 0
	global_load_lds_dwordx4 v132, s[100:101]
	s_mov_b32 m0, s59
	s_nop 0
	global_load_lds_dwordx4 v134, s[100:101]
	s_add_i32 m0, s10, 0xc000
	s_nop 0
	global_load_lds_dwordx4 v138, s[56:57]
	s_add_i32 m0, s10, 0xe000
	s_nop 0
	global_load_lds_dwordx4 v140, s[56:57]
	s_nop 0
	s_nop 0
	s_setprio 1
	s_waitcnt vmcnt(8)
	s_waitcnt lgkmcnt(0)
	s_barrier
	v_mfma_f32_16x16x32_bf16 v[128:131], v[142:145], v[178:181], v[128:131]
	v_mfma_f32_16x16x32_bf16 v[128:131], v[150:153], v[182:185], v[128:131]
	v_mfma_f32_16x16x32_bf16 v[124:127], v[154:157], v[178:181], v[124:127]
	v_mfma_f32_16x16x32_bf16 v[124:127], v[158:161], v[182:185], v[124:127]
	v_mfma_f32_16x16x32_bf16 v[108:111], v[154:157], v[186:189], v[108:111]
	v_mfma_f32_16x16x32_bf16 v[108:111], v[158:161], v[190:193], v[108:111]
	v_mfma_f32_16x16x32_bf16 v[112:115], v[142:145], v[186:189], v[112:115]
	v_mfma_f32_16x16x32_bf16 v[112:115], v[150:153], v[190:193], v[112:115]
	v_mfma_f32_16x16x32_bf16 v[96:99], v[142:145], v[194:197], v[96:99]
	v_mfma_f32_16x16x32_bf16 v[96:99], v[150:153], v[198:201], v[96:99]
	v_mfma_f32_16x16x32_bf16 v[92:95], v[154:157], v[194:197], v[92:95]
	v_mfma_f32_16x16x32_bf16 v[92:95], v[158:161], v[198:201], v[92:95]
	v_mfma_f32_16x16x32_bf16 v[76:79], v[154:157], v[202:205], v[76:79]
	v_mfma_f32_16x16x32_bf16 v[76:79], v[158:161], v[206:209], v[76:79]
	v_mfma_f32_16x16x32_bf16 v[80:83], v[142:145], v[202:205], v[80:83]
	v_mfma_f32_16x16x32_bf16 v[80:83], v[150:153], v[206:209], v[80:83]
	s_setprio 0
	s_setprio 1
	v_mfma_f32_16x16x32_bf16 v[120:123], v[162:165], v[178:181], v[120:123]
	v_mfma_f32_16x16x32_bf16 v[120:123], v[166:169], v[182:185], v[120:123]
	v_mfma_f32_16x16x32_bf16 v[116:119], v[170:173], v[178:181], v[116:119]
	v_mfma_f32_16x16x32_bf16 v[116:119], v[174:177], v[182:185], v[116:119]
	v_mfma_f32_16x16x32_bf16 v[100:103], v[170:173], v[186:189], v[100:103]
	v_mfma_f32_16x16x32_bf16 v[100:103], v[174:177], v[190:193], v[100:103]
	v_mfma_f32_16x16x32_bf16 v[104:107], v[162:165], v[186:189], v[104:107]
	v_mfma_f32_16x16x32_bf16 v[104:107], v[166:169], v[190:193], v[104:107]
	v_mfma_f32_16x16x32_bf16 v[88:91], v[162:165], v[194:197], v[88:91]
	v_mfma_f32_16x16x32_bf16 v[88:91], v[166:169], v[198:201], v[88:91]
	v_mfma_f32_16x16x32_bf16 v[84:87], v[170:173], v[194:197], v[84:87]
	v_mfma_f32_16x16x32_bf16 v[84:87], v[174:177], v[198:201], v[84:87]
	v_mfma_f32_16x16x32_bf16 v[68:71], v[170:173], v[202:205], v[68:71]
	v_mfma_f32_16x16x32_bf16 v[68:71], v[174:177], v[206:209], v[68:71]
	v_mfma_f32_16x16x32_bf16 v[72:75], v[162:165], v[202:205], v[72:75]
	v_mfma_f32_16x16x32_bf16 v[72:75], v[166:169], v[206:209], v[72:75]
	s_barrier
	s_setprio 0
	ds_read_b128 v[178:181], v149 offset:16384
	ds_read_b128 v[182:185], v149 offset:17408
	ds_read_b128 v[186:189], v149 offset:18432
	ds_read_b128 v[190:193], v149 offset:19456
	ds_read_b128 v[194:197], v149 offset:20480
	ds_read_b128 v[198:201], v149 offset:21504
	ds_read_b128 v[202:205], v149 offset:22528
	ds_read_b128 v[206:209], v149 offset:23552
	s_add_i32 s63, s63, s9
	s_mov_b32 m0, s63
	s_nop 0
	global_load_lds_dwordx4 v2, s[0:1]
	s_add_i32 m0, s63, 0x2000
	s_add_u32 s64, s0, 0x100000
	s_addc_u32 s65, s1, 0
	s_add_i32 s63, s66, s9
	global_load_lds_dwordx4 v136, s[0:1]
	s_mov_b32 m0, s63
	s_nop 0
	global_load_lds_dwordx4 v2, s[64:65]
	s_add_i32 m0, s63, 0x2000
	s_nop 0
	global_load_lds_dwordx4 v136, s[64:65]
	s_setprio 1
	s_waitcnt vmcnt(6)
	s_waitcnt lgkmcnt(0)
	s_barrier
	v_mfma_f32_16x16x32_bf16 v[64:67], v[142:145], v[178:181], v[64:67]
	v_mfma_f32_16x16x32_bf16 v[64:67], v[150:153], v[182:185], v[64:67]
	v_mfma_f32_16x16x32_bf16 v[60:63], v[154:157], v[178:181], v[60:63]
	v_mfma_f32_16x16x32_bf16 v[60:63], v[158:161], v[182:185], v[60:63]
	v_mfma_f32_16x16x32_bf16 v[44:47], v[154:157], v[186:189], v[44:47]
	v_mfma_f32_16x16x32_bf16 v[44:47], v[158:161], v[190:193], v[44:47]
	v_mfma_f32_16x16x32_bf16 v[48:51], v[142:145], v[186:189], v[48:51]
	v_mfma_f32_16x16x32_bf16 v[48:51], v[150:153], v[190:193], v[48:51]
	v_mfma_f32_16x16x32_bf16 v[32:35], v[142:145], v[194:197], v[32:35]
	v_mfma_f32_16x16x32_bf16 v[32:35], v[150:153], v[198:201], v[32:35]
	v_mfma_f32_16x16x32_bf16 v[28:31], v[154:157], v[194:197], v[28:31]
	v_mfma_f32_16x16x32_bf16 v[28:31], v[158:161], v[198:201], v[28:31]
	v_mfma_f32_16x16x32_bf16 v[12:15], v[154:157], v[202:205], v[12:15]
	v_mfma_f32_16x16x32_bf16 v[12:15], v[158:161], v[206:209], v[12:15]
	v_mfma_f32_16x16x32_bf16 v[16:19], v[142:145], v[202:205], v[16:19]
	v_mfma_f32_16x16x32_bf16 v[16:19], v[150:153], v[206:209], v[16:19]
	s_setprio 0
	s_setprio 1
	v_mfma_f32_16x16x32_bf16 v[56:59], v[162:165], v[178:181], v[56:59]
	v_mfma_f32_16x16x32_bf16 v[56:59], v[166:169], v[182:185], v[56:59]
	v_mfma_f32_16x16x32_bf16 v[52:55], v[170:173], v[178:181], v[52:55]
	v_mfma_f32_16x16x32_bf16 v[52:55], v[174:177], v[182:185], v[52:55]
	v_mfma_f32_16x16x32_bf16 v[36:39], v[170:173], v[186:189], v[36:39]
	v_mfma_f32_16x16x32_bf16 v[36:39], v[174:177], v[190:193], v[36:39]
	v_mfma_f32_16x16x32_bf16 v[40:43], v[162:165], v[186:189], v[40:43]
	v_mfma_f32_16x16x32_bf16 v[40:43], v[166:169], v[190:193], v[40:43]
	v_mfma_f32_16x16x32_bf16 v[24:27], v[162:165], v[194:197], v[24:27]
	v_mfma_f32_16x16x32_bf16 v[24:27], v[166:169], v[198:201], v[24:27]
	v_mfma_f32_16x16x32_bf16 v[20:23], v[170:173], v[194:197], v[20:23]
	v_mfma_f32_16x16x32_bf16 v[20:23], v[174:177], v[198:201], v[20:23]
	v_mfma_f32_16x16x32_bf16 v[4:7], v[170:173], v[202:205], v[4:7]
	v_mfma_f32_16x16x32_bf16 v[4:7], v[174:177], v[206:209], v[4:7]
	v_mfma_f32_16x16x32_bf16 v[8:11], v[162:165], v[202:205], v[8:11]
	v_mfma_f32_16x16x32_bf16 v[8:11], v[166:169], v[206:209], v[8:11]
	s_barrier
; #define PG8_STAGE(bufoff, gbase, voff) do { _Pragma("unroll") for (int _i = 0; _i < 2; ++_i) \
;         __builtin_amdgcn_global_load_lds((const unsigned*)((const char*)(gbase) + (voff)[_i]), (PG8_LAS unsigned*)(lds + (bufoff) + ldsw + _i * 8192), 16, 0, 0); } while (0)
; #define PG8_LDA(dst, b, h) do { _Pragma("unroll") for (int m = 0; m < 4; ++m) _Pragma("unroll") for (int k = 0; k < 2; ++k) dst[m][k] = *(const PG8_LAS bf16x8*)(lds + PG8_SA(b, h) + aoff + m * 2048 + k * 1024); } while (0)
; #define PG8_LDB(dst, b, h) do { _Pragma("unroll") for (int n = 0; n < 2; ++n) _Pragma("unroll") for (int k = 0; k < 2; ++k) dst[n][k] = *(const PG8_LAS bf16x8*)(lds + PG8_SB(b, h) + boff + n * 2048 + k * 1024); } while (0)
; #define PG8_MMA(ai, bj, At, Bt) do { __builtin_amdgcn_s_setprio(1); _Pragma("unroll") for (int m = 0; m < 4; ++m) _Pragma("unroll") for (int n = 0; n < 2; ++n) _Pragma("unroll") for (int k = 0; k < 2; ++k) \
;         acc[ai][bj][m][n] = __builtin_amdgcn_mfma_f32_16x16x32_bf16(Bt[n][k], At[m][k], acc[ai][bj][m][n], 0, 0, 0); __builtin_amdgcn_s_setprio(0); } while (0)
; #define PG8_WAIT_V(n) asm volatile("s_waitcnt vmcnt(" #n ")" ::: "memory")
; #define PG8_WAIT_L(n) asm volatile("s_waitcnt lgkmcnt(" #n ")" ::: "memory")
; #define PG8_BAR __builtin_amdgcn_s_barrier()
; #define PG8_SCHED __builtin_amdgcn_sched_barrier(0)
; template <class Epi, class Sched, bool ALIGN_EPI = false, bool SP2 = false>
; __device__ __forceinline__ void gemm_phase(PG8_LAS unsigned char* lds, const Gemm g, const Sched& S, const Epi& E) {
;     ...
;             PG8_LDB(B0, 1, 0); PG8_LDB(B1, 1, 1); PG8_SCHED; PG8_LDA(At, 1, 0); PG8_STAGE(PG8_SA(0, 1), a2 + hstep, voffA);
;             PG8_WAIT_V(8); PG8_WAIT_L(0); PG8_BAR; PG8_MMA(0, 0, At, B0); PG8_MMA(0, 1, At, B1); PG8_BAR; PG8_SCHED;
;             PG8_LDA(At, 1, 1); PG8_STAGE(PG8_SB(1, 0), b3, voffB); PG8_STAGE(PG8_SB(1, 1), b3 + hstep, voffB); PG8_STAGE(PG8_SA(1, 0), a3, voffA);
;             PG8_WAIT_V(8); PG8_WAIT_L(0); PG8_BAR; PG8_MMA(1, 0, At, B0); PG8_MMA(1, 1, At, B1); PG8_BAR; PG8_SCHED;
	s_setprio 0
	ds_read_b128 v[142:145], v210 offset:32768
	ds_read_b128 v[150:153], v210 offset:33792
	ds_read_b128 v[154:157], v210 offset:34816
	ds_read_b128 v[158:161], v210 offset:35840
	ds_read_b128 v[162:165], v210 offset:49152
	ds_read_b128 v[166:169], v210 offset:50176
	ds_read_b128 v[170:173], v210 offset:51200
	ds_read_b128 v[174:177], v210 offset:52224
	ds_read_b128 v[178:181], v149 offset:32768
	ds_read_b128 v[182:185], v149 offset:33792
	ds_read_b128 v[186:189], v149 offset:34816
	ds_read_b128 v[190:193], v149 offset:35840
	ds_read_b128 v[194:197], v149 offset:36864
	ds_read_b128 v[198:201], v149 offset:37888
	ds_read_b128 v[202:205], v149 offset:38912
	ds_read_b128 v[206:209], v149 offset:39936
	s_add_i32 s63, 0, 0x18000
	s_add_i32 s64, 0, 0x1c000
	s_mov_b32 m0, s10
	s_nop 0
	global_load_lds_dwordx4 v132, s[26:27]
	s_mov_b32 m0, s11
	s_nop 0
	global_load_lds_dwordx4 v134, s[26:27]
	s_add_u32 s26, s26, 0x100000
	s_addc_u32 s27, s27, 0
	s_mov_b32 m0, s25
	s_nop 0
	global_load_lds_dwordx4 v132, s[26:27]
	s_mov_b32 m0, s55
	s_nop 0
	global_load_lds_dwordx4 v134, s[26:27]
	s_nop 0
	s_setprio 1
	s_waitcnt vmcnt(8)
	s_waitcnt lgkmcnt(0)
	s_barrier
	v_mfma_f32_16x16x32_bf16 v[128:131], v[142:145], v[178:181], v[128:131]
	v_mfma_f32_16x16x32_bf16 v[128:131], v[150:153], v[182:185], v[128:131]
	v_mfma_f32_16x16x32_bf16 v[124:127], v[154:157], v[178:181], v[124:127]
	v_mfma_f32_16x16x32_bf16 v[124:127], v[158:161], v[182:185], v[124:127]
	v_mfma_f32_16x16x32_bf16 v[108:111], v[154:157], v[186:189], v[108:111]
	v_mfma_f32_16x16x32_bf16 v[108:111], v[158:161], v[190:193], v[108:111]
	v_mfma_f32_16x16x32_bf16 v[112:115], v[142:145], v[186:189], v[112:115]
	v_mfma_f32_16x16x32_bf16 v[112:115], v[150:153], v[190:193], v[112:115]
	v_mfma_f32_16x16x32_bf16 v[96:99], v[142:145], v[194:197], v[96:99]
	v_mfma_f32_16x16x32_bf16 v[96:99], v[150:153], v[198:201], v[96:99]
	v_mfma_f32_16x16x32_bf16 v[92:95], v[154:157], v[194:197], v[92:95]
	v_mfma_f32_16x16x32_bf16 v[92:95], v[158:161], v[198:201], v[92:95]
	v_mfma_f32_16x16x32_bf16 v[76:79], v[154:157], v[202:205], v[76:79]
	v_mfma_f32_16x16x32_bf16 v[76:79], v[158:161], v[206:209], v[76:79]
	v_mfma_f32_16x16x32_bf16 v[80:83], v[142:145], v[202:205], v[80:83]
	v_mfma_f32_16x16x32_bf16 v[80:83], v[150:153], v[206:209], v[80:83]
	s_setprio 0
	s_setprio 1
	v_mfma_f32_16x16x32_bf16 v[120:123], v[162:165], v[178:181], v[120:123]
	v_mfma_f32_16x16x32_bf16 v[120:123], v[166:169], v[182:185], v[120:123]
	v_mfma_f32_16x16x32_bf16 v[116:119], v[170:173], v[178:181], v[116:119]
	v_mfma_f32_16x16x32_bf16 v[116:119], v[174:177], v[182:185], v[116:119]
	v_mfma_f32_16x16x32_bf16 v[100:103], v[170:173], v[186:189], v[100:103]
	v_mfma_f32_16x16x32_bf16 v[100:103], v[174:177], v[190:193], v[100:103]
	v_mfma_f32_16x16x32_bf16 v[104:107], v[162:165], v[186:189], v[104:107]
	v_mfma_f32_16x16x32_bf16 v[104:107], v[166:169], v[190:193], v[104:107]
	v_mfma_f32_16x16x32_bf16 v[88:91], v[162:165], v[194:197], v[88:91]
	v_mfma_f32_16x16x32_bf16 v[88:91], v[166:169], v[198:201], v[88:91]
	v_mfma_f32_16x16x32_bf16 v[84:87], v[170:173], v[194:197], v[84:87]
	v_mfma_f32_16x16x32_bf16 v[84:87], v[174:177], v[198:201], v[84:87]
	v_mfma_f32_16x16x32_bf16 v[68:71], v[170:173], v[202:205], v[68:71]
	v_mfma_f32_16x16x32_bf16 v[68:71], v[174:177], v[206:209], v[68:71]
	v_mfma_f32_16x16x32_bf16 v[72:75], v[162:165], v[202:205], v[72:75]
	v_mfma_f32_16x16x32_bf16 v[72:75], v[166:169], v[206:209], v[72:75]
	s_barrier
	s_setprio 0
	ds_read_b128 v[178:181], v149 offset:49152
	ds_read_b128 v[182:185], v149 offset:50176
	ds_read_b128 v[186:189], v149 offset:51200
	ds_read_b128 v[190:193], v149 offset:52224
	ds_read_b128 v[194:197], v149 offset:53248
	ds_read_b128 v[198:201], v149 offset:54272
	ds_read_b128 v[202:205], v149 offset:55296
	ds_read_b128 v[206:209], v149 offset:56320
	s_add_i32 s26, s63, s9
	s_mov_b32 m0, s26
	s_add_u32 s0, s0, 0x80
	s_addc_u32 s1, s1, 0
	global_load_lds_dwordx4 v2, s[0:1]
	s_add_i32 m0, s26, 0x2000
	s_add_i32 s26, s64, s9
	global_load_lds_dwordx4 v136, s[0:1]
	s_add_u32 s0, s0, 0x100000
	s_addc_u32 s1, s1, 0
	s_mov_b32 m0, s26
	s_nop 0
	global_load_lds_dwordx4 v2, s[0:1]
	s_add_i32 m0, s26, 0x2000
	s_nop 0
	global_load_lds_dwordx4 v136, s[0:1]
	s_setprio 1
	s_waitcnt vmcnt(6)
	s_waitcnt lgkmcnt(0)
	s_barrier
	v_mfma_f32_16x16x32_bf16 v[64:67], v[142:145], v[178:181], v[64:67]
	v_mfma_f32_16x16x32_bf16 v[64:67], v[150:153], v[182:185], v[64:67]
	v_mfma_f32_16x16x32_bf16 v[60:63], v[154:157], v[178:181], v[60:63]
	v_mfma_f32_16x16x32_bf16 v[60:63], v[158:161], v[182:185], v[60:63]
	v_mfma_f32_16x16x32_bf16 v[44:47], v[154:157], v[186:189], v[44:47]
	v_mfma_f32_16x16x32_bf16 v[44:47], v[158:161], v[190:193], v[44:47]
	v_mfma_f32_16x16x32_bf16 v[48:51], v[142:145], v[186:189], v[48:51]
	v_mfma_f32_16x16x32_bf16 v[48:51], v[150:153], v[190:193], v[48:51]
	v_mfma_f32_16x16x32_bf16 v[32:35], v[142:145], v[194:197], v[32:35]
	v_mfma_f32_16x16x32_bf16 v[32:35], v[150:153], v[198:201], v[32:35]
	v_mfma_f32_16x16x32_bf16 v[28:31], v[154:157], v[194:197], v[28:31]
	v_mfma_f32_16x16x32_bf16 v[28:31], v[158:161], v[198:201], v[28:31]
	v_mfma_f32_16x16x32_bf16 v[12:15], v[154:157], v[202:205], v[12:15]
	v_mfma_f32_16x16x32_bf16 v[12:15], v[158:161], v[206:209], v[12:15]
	v_mfma_f32_16x16x32_bf16 v[16:19], v[142:145], v[202:205], v[16:19]
	v_mfma_f32_16x16x32_bf16 v[16:19], v[150:153], v[206:209], v[16:19]
	s_setprio 0
	s_setprio 1
	s_add_i32 s62, s62, 2
	s_add_u32 s56, s56, 0x100
	s_addc_u32 s57, s57, 0
	s_add_u32 s47, s47, 0x100
	s_addc_u32 s49, s49, 0
	s_nop 0
	v_mfma_f32_16x16x32_bf16 v[56:59], v[162:165], v[178:181], v[56:59]
	v_mfma_f32_16x16x32_bf16 v[56:59], v[166:169], v[182:185], v[56:59]
	v_mfma_f32_16x16x32_bf16 v[52:55], v[170:173], v[178:181], v[52:55]
	v_mfma_f32_16x16x32_bf16 v[52:55], v[174:177], v[182:185], v[52:55]
	v_mfma_f32_16x16x32_bf16 v[36:39], v[170:173], v[186:189], v[36:39]
	v_mfma_f32_16x16x32_bf16 v[36:39], v[174:177], v[190:193], v[36:39]
	v_mfma_f32_16x16x32_bf16 v[40:43], v[162:165], v[186:189], v[40:43]
	v_mfma_f32_16x16x32_bf16 v[40:43], v[166:169], v[190:193], v[40:43]
	v_mfma_f32_16x16x32_bf16 v[24:27], v[162:165], v[194:197], v[24:27]
	v_mfma_f32_16x16x32_bf16 v[24:27], v[166:169], v[198:201], v[24:27]
	v_mfma_f32_16x16x32_bf16 v[20:23], v[170:173], v[194:197], v[20:23]
	v_mfma_f32_16x16x32_bf16 v[20:23], v[174:177], v[198:201], v[20:23]
	v_mfma_f32_16x16x32_bf16 v[4:7], v[170:173], v[202:205], v[4:7]
	v_mfma_f32_16x16x32_bf16 v[4:7], v[174:177], v[206:209], v[4:7]
	v_mfma_f32_16x16x32_bf16 v[8:11], v[162:165], v[202:205], v[8:11]
	v_mfma_f32_16x16x32_bf16 v[8:11], v[166:169], v[206:209], v[8:11]
	s_barrier
	s_cmp_gt_u32 s62, 61
	s_cbranch_scc0 .LBB0_1624
	s_setprio 0
	s_and_b64 vcc, exec, s[44:45]
	s_cbranch_vccz .LBB0_1627
	s_barrier
